# P0 weight transposes with k-scale: 16 weight + 16 scale loads in flight per batch instead of load-wait per element
# speedup vs baseline: 1.0209x; 1.0099x over previous
; #define LAS __attribute__((address_space(3)))
; __device__ __forceinline__ void transpose_item(const float* W, int ldw, int K, bf16_t* WT, const float* kscale, LAS float* scr, int k0, int srccol0, int dstrow0, int lane) {
; #pragma unroll 8
;     for (int i = 0; i < 32; ++i) { const int kk = 2 * i + (lane >> 5); float v = W[(size_t)(k0 + kk) * ldw + srccol0 + (lane & 31)]; if (kscale) v *= kscale[k0 + kk]; scr[kk * 33 + (lane & 31)] = v; }
;     asm volatile("s_waitcnt lgkmcnt(0)" ::: "memory");
; __device__ __forceinline__ void p0_prologue(const Args& a, LAS unsigned char* lds, int gw, int NGW, int lane, int wave) {
;     ...
;         if (r < I_UP) { const int kb = r / 176, nb = r % 176; const int dst = nb * 32; const int pn = dst >> 8, i = dst & 255; const int src = i < 128 ? pn * 128 + i : DFF + pn * 128 + (i - 128);
;             transpose_item(a.in[I_WUP], NUP, 1024, WupT, a.in[I_PREFFN], scr, kb * 64, src, dst, lane); continue; }
.LBB0_16:
	s_and_b64 vcc, exec, s[2:3]
	s_cbranch_vccz .LBB0_37
	s_add_i32 s2, s16, 0xfa00
	s_and_b32 s3, s2, 0xffff
	s_mul_i32 s4, s3, 0xba2f
	s_lshr_b32 s4, s4, 23
	s_mul_i32 s12, s4, 0xb0
	s_sub_i32 s2, s2, s12
	s_and_b32 s2, s2, 0xffff
	s_lshl_b32 s17, s2, 5
	s_lshl_b32 s2, s2, 4
	s_and_b32 s12, s17, 0xe0
	s_and_b32 s2, s2, 0xf80
	s_or_b32 s13, s2, s12
	s_add_i32 s2, s12, s2
	s_addk_i32 s2, 0xa80
	s_cmpk_lt_u32 s12, 0x80
	s_cselect_b32 s2, s13, s2
	s_lshl_b32 s18, s4, 6
	v_or_b32_e32 v6, s18, v50
	s_lshl_b32 s4, s2, 2
	v_mul_u32_u24_e32 v6, 0x5800, v6
	v_lshl_add_u64 v[28:29], s[4:5], 0, v[6:7]
	v_or_b32_e32 v6, s18, v51
	v_mul_u32_u24_e32 v6, 0x5800, v6
	v_lshl_add_u64 v[32:33], s[4:5], 0, v[6:7]
	v_or_b32_e32 v6, s18, v52
	v_mul_u32_u24_e32 v6, 0x5800, v6
	v_lshl_add_u64 v[36:37], s[4:5], 0, v[6:7]
	v_or_b32_e32 v6, s18, v53
	v_mul_u32_u24_e32 v6, 0x5800, v6
	v_lshl_add_u64 v[38:39], s[4:5], 0, v[6:7]
	v_or_b32_e32 v6, s18, v54
	v_mul_u32_u24_e32 v6, 0x5800, v6
	v_lshl_add_u64 v[40:41], s[4:5], 0, v[6:7]
	v_or_b32_e32 v6, s18, v55
	s_mul_hi_u32 s12, s3, 0x1745d18
	v_mul_u32_u24_e32 v6, 0x5800, v6
	s_mul_i32 s2, s12, 0x160000
	v_lshl_add_u64 v[42:43], s[4:5], 0, v[6:7]
	v_or_b32_e32 v6, s18, v56
	s_or_b32 s2, s2, s4
	s_mov_b32 s3, s5
	v_mul_u32_u24_e32 v6, 0x5800, v6
	v_lshl_add_u64 v[30:31], v[24:25], 0, s[2:3]
	s_lshl_b32 s2, s12, 8
	v_lshl_add_u64 v[44:45], s[4:5], 0, v[6:7]
	v_lshl_add_u64 v[28:29], v[22:23], 0, v[28:29]
	v_lshl_add_u64 v[32:33], v[22:23], 0, v[32:33]
	v_lshl_add_u64 v[34:35], v[26:27], 0, s[2:3]
	v_lshl_add_u64 v[36:37], v[22:23], 0, v[36:37]
	v_lshl_add_u64 v[38:39], v[22:23], 0, v[38:39]
	v_lshl_add_u64 v[40:41], v[22:23], 0, v[40:41]
	v_lshl_add_u64 v[42:43], v[22:23], 0, v[42:43]
	v_lshl_add_u64 v[44:45], v[22:23], 0, v[44:45]
	s_mov_b64 s[12:13], 0
	v_mov_b32_e32 v6, v49
	s_and_b64 s[36:37], s[6:7], exec
	s_cmp_eq_u64 s[36:37], exec
	s_cbranch_scc0 .LBB0_19
	s_mov_b32 s41, 0
	s_mov_b32 s40, 0x0
	v_lshl_add_u64 v[100:101], v[30:31], 0, s[40:41]
	global_load_dword v108, v[100:101], off
	v_lshl_add_u64 v[102:103], v[44:45], 0, s[40:41]
	global_load_dword v109, v[102:103], off
	v_lshl_add_u64 v[104:105], v[42:43], 0, s[40:41]
	global_load_dword v110, v[104:105], off
	v_lshl_add_u64 v[106:107], v[40:41], 0, s[40:41]
	global_load_dword v111, v[106:107], off
	v_lshl_add_u64 v[100:101], v[38:39], 0, s[40:41]
	global_load_dword v112, v[100:101], off
	v_lshl_add_u64 v[102:103], v[36:37], 0, s[40:41]
	global_load_dword v113, v[102:103], off
	v_lshl_add_u64 v[104:105], v[32:33], 0, s[40:41]
	global_load_dword v114, v[104:105], off
	v_lshl_add_u64 v[106:107], v[28:29], 0, s[40:41]
	global_load_dword v115, v[106:107], off
	s_mov_b32 s40, 0x58000
	v_lshl_add_u64 v[100:101], v[30:31], 0, s[40:41]
	global_load_dword v116, v[100:101], off
	v_lshl_add_u64 v[102:103], v[44:45], 0, s[40:41]
	global_load_dword v117, v[102:103], off
	v_lshl_add_u64 v[104:105], v[42:43], 0, s[40:41]
	global_load_dword v118, v[104:105], off
	v_lshl_add_u64 v[106:107], v[40:41], 0, s[40:41]
	global_load_dword v119, v[106:107], off
	v_lshl_add_u64 v[100:101], v[38:39], 0, s[40:41]
	global_load_dword v120, v[100:101], off
	v_lshl_add_u64 v[102:103], v[36:37], 0, s[40:41]
	global_load_dword v121, v[102:103], off
	v_lshl_add_u64 v[104:105], v[32:33], 0, s[40:41]
	global_load_dword v122, v[104:105], off
	v_lshl_add_u64 v[106:107], v[28:29], 0, s[40:41]
	global_load_dword v123, v[106:107], off
	global_load_dword v124, v[34:35], off offset:-56
	global_load_dword v125, v[34:35], off offset:-48
	global_load_dword v126, v[34:35], off offset:-40
	global_load_dword v127, v[34:35], off offset:-32
	global_load_dword v128, v[34:35], off offset:-24
	global_load_dword v129, v[34:35], off offset:-16
	global_load_dword v130, v[34:35], off offset:-8
	global_load_dword v131, v[34:35], off
	global_load_dword v132, v[34:35], off offset:8
	global_load_dword v133, v[34:35], off offset:16
	global_load_dword v134, v[34:35], off offset:24
	global_load_dword v135, v[34:35], off offset:32
	global_load_dword v136, v[34:35], off offset:40
	global_load_dword v137, v[34:35], off offset:48
	global_load_dword v138, v[34:35], off offset:56
	global_load_dword v139, v[34:35], off offset:64
	s_waitcnt vmcnt(15)
	v_mul_f32_e32 v108, v108, v124
	ds_write_b32 v6, v108
	s_waitcnt vmcnt(14)
	v_mul_f32_e32 v109, v109, v125
	ds_write_b32 v6, v109 offset:264
	s_waitcnt vmcnt(13)
	v_mul_f32_e32 v110, v110, v126
	ds_write_b32 v6, v110 offset:528
	s_waitcnt vmcnt(12)
	v_mul_f32_e32 v111, v111, v127
	ds_write_b32 v6, v111 offset:792
	s_waitcnt vmcnt(11)
	v_mul_f32_e32 v112, v112, v128
	ds_write_b32 v6, v112 offset:1056
	s_waitcnt vmcnt(10)
; #define LAS __attribute__((address_space(3)))
; __device__ __forceinline__ void transpose_item(const float* W, int ldw, int K, bf16_t* WT, const float* kscale, LAS float* scr, int k0, int srccol0, int dstrow0, int lane) {
; #pragma unroll 8
;     for (int i = 0; i < 32; ++i) { const int kk = 2 * i + (lane >> 5); float v = W[(size_t)(k0 + kk) * ldw + srccol0 + (lane & 31)]; if (kscale) v *= kscale[k0 + kk]; scr[kk * 33 + (lane & 31)] = v; }
;     asm volatile("s_waitcnt lgkmcnt(0)" ::: "memory");
	v_mul_f32_e32 v113, v113, v129
	ds_write_b32 v6, v113 offset:1320
	s_waitcnt vmcnt(9)
	v_mul_f32_e32 v114, v114, v130
	ds_write_b32 v6, v114 offset:1584
	s_waitcnt vmcnt(8)
	v_mul_f32_e32 v115, v115, v131
	ds_write_b32 v6, v115 offset:1848
	s_waitcnt vmcnt(7)
	v_mul_f32_e32 v116, v116, v132
	ds_write_b32 v6, v116 offset:2112
	s_waitcnt vmcnt(6)
	v_mul_f32_e32 v117, v117, v133
	ds_write_b32 v6, v117 offset:2376
	s_waitcnt vmcnt(5)
	v_mul_f32_e32 v118, v118, v134
	ds_write_b32 v6, v118 offset:2640
	s_waitcnt vmcnt(4)
	v_mul_f32_e32 v119, v119, v135
	ds_write_b32 v6, v119 offset:2904
	s_waitcnt vmcnt(3)
	v_mul_f32_e32 v120, v120, v136
	ds_write_b32 v6, v120 offset:3168
	s_waitcnt vmcnt(2)
	v_mul_f32_e32 v121, v121, v137
	ds_write_b32 v6, v121 offset:3432
	s_waitcnt vmcnt(1)
	v_mul_f32_e32 v122, v122, v138
	ds_write_b32 v6, v122 offset:3696
	s_waitcnt vmcnt(0)
	v_mul_f32_e32 v123, v123, v139
	ds_write_b32 v6, v123 offset:3960
	s_mov_b32 s40, 0xb0000
	v_lshl_add_u64 v[100:101], v[30:31], 0, s[40:41]
	global_load_dword v108, v[100:101], off
	v_lshl_add_u64 v[102:103], v[44:45], 0, s[40:41]
	global_load_dword v109, v[102:103], off
	v_lshl_add_u64 v[104:105], v[42:43], 0, s[40:41]
	global_load_dword v110, v[104:105], off
	v_lshl_add_u64 v[106:107], v[40:41], 0, s[40:41]
	global_load_dword v111, v[106:107], off
	v_lshl_add_u64 v[100:101], v[38:39], 0, s[40:41]
	global_load_dword v112, v[100:101], off
	v_lshl_add_u64 v[102:103], v[36:37], 0, s[40:41]
	global_load_dword v113, v[102:103], off
	v_lshl_add_u64 v[104:105], v[32:33], 0, s[40:41]
	global_load_dword v114, v[104:105], off
	v_lshl_add_u64 v[106:107], v[28:29], 0, s[40:41]
	global_load_dword v115, v[106:107], off
	s_mov_b32 s40, 0x108000
	v_lshl_add_u64 v[100:101], v[30:31], 0, s[40:41]
	global_load_dword v116, v[100:101], off
	v_lshl_add_u64 v[102:103], v[44:45], 0, s[40:41]
	global_load_dword v117, v[102:103], off
	v_lshl_add_u64 v[104:105], v[42:43], 0, s[40:41]
	global_load_dword v118, v[104:105], off
	v_lshl_add_u64 v[106:107], v[40:41], 0, s[40:41]
	global_load_dword v119, v[106:107], off
	v_lshl_add_u64 v[100:101], v[38:39], 0, s[40:41]
	global_load_dword v120, v[100:101], off
	v_lshl_add_u64 v[102:103], v[36:37], 0, s[40:41]
	global_load_dword v121, v[102:103], off
	v_lshl_add_u64 v[104:105], v[32:33], 0, s[40:41]
	global_load_dword v122, v[104:105], off
	v_lshl_add_u64 v[106:107], v[28:29], 0, s[40:41]
	global_load_dword v123, v[106:107], off
	global_load_dword v124, v[34:35], off offset:72
	global_load_dword v125, v[34:35], off offset:80
	global_load_dword v126, v[34:35], off offset:88
	global_load_dword v127, v[34:35], off offset:96
	global_load_dword v128, v[34:35], off offset:104
	global_load_dword v129, v[34:35], off offset:112
	global_load_dword v130, v[34:35], off offset:120
	global_load_dword v131, v[34:35], off offset:128
	global_load_dword v132, v[34:35], off offset:136
	global_load_dword v133, v[34:35], off offset:144
	global_load_dword v134, v[34:35], off offset:152
	global_load_dword v135, v[34:35], off offset:160
	global_load_dword v136, v[34:35], off offset:168
	global_load_dword v137, v[34:35], off offset:176
	global_load_dword v138, v[34:35], off offset:184
	global_load_dword v139, v[34:35], off offset:192
	s_waitcnt vmcnt(15)
	v_mul_f32_e32 v108, v108, v124
	ds_write_b32 v6, v108 offset:4224
	s_waitcnt vmcnt(14)
	v_mul_f32_e32 v109, v109, v125
	ds_write_b32 v6, v109 offset:4488
	s_waitcnt vmcnt(13)
	v_mul_f32_e32 v110, v110, v126
	ds_write_b32 v6, v110 offset:4752
	s_waitcnt vmcnt(12)
	v_mul_f32_e32 v111, v111, v127
	ds_write_b32 v6, v111 offset:5016
	s_waitcnt vmcnt(11)
	v_mul_f32_e32 v112, v112, v128
	ds_write_b32 v6, v112 offset:5280
	s_waitcnt vmcnt(10)
	v_mul_f32_e32 v113, v113, v129
	ds_write_b32 v6, v113 offset:5544
	s_waitcnt vmcnt(9)
	v_mul_f32_e32 v114, v114, v130
	ds_write_b32 v6, v114 offset:5808
	s_waitcnt vmcnt(8)
	v_mul_f32_e32 v115, v115, v131
	ds_write_b32 v6, v115 offset:6072
	s_waitcnt vmcnt(7)
	v_mul_f32_e32 v116, v116, v132
	ds_write_b32 v6, v116 offset:6336
	s_waitcnt vmcnt(6)
	v_mul_f32_e32 v117, v117, v133
	ds_write_b32 v6, v117 offset:6600
	s_waitcnt vmcnt(5)
	v_mul_f32_e32 v118, v118, v134
	ds_write_b32 v6, v118 offset:6864
	s_waitcnt vmcnt(4)
	v_mul_f32_e32 v119, v119, v135
	ds_write_b32 v6, v119 offset:7128
	s_waitcnt vmcnt(3)
	v_mul_f32_e32 v120, v120, v136
	ds_write_b32 v6, v120 offset:7392
	s_waitcnt vmcnt(2)
	v_mul_f32_e32 v121, v121, v137
	ds_write_b32 v6, v121 offset:7656
	s_waitcnt vmcnt(1)
	v_mul_f32_e32 v122, v122, v138
	ds_write_b32 v6, v122 offset:7920
	s_waitcnt vmcnt(0)
	v_mul_f32_e32 v123, v123, v139
	ds_write_b32 v6, v123 offset:8184
	s_branch .LBB0_36

; #define LAS __attribute__((address_space(3)))
; __device__ __forceinline__ void transpose_item(const float* W, int ldw, int K, bf16_t* WT, const float* kscale, LAS float* scr, int k0, int srccol0, int dstrow0, int lane) {
; #pragma unroll 8
;     for (int i = 0; i < 32; ++i) { const int kk = 2 * i + (lane >> 5); float v = W[(size_t)(k0 + kk) * ldw + srccol0 + (lane & 31)]; if (kscale) v *= kscale[k0 + kk]; scr[kk * 33 + (lane & 31)] = v; }
;     asm volatile("s_waitcnt lgkmcnt(0)" ::: "memory");
; __device__ __forceinline__ void p0_prologue(const Args& a, LAS unsigned char* lds, int gw, int NGW, int lane, int wave) {
;     ...
;         if (r < I_IN) { const int kb = r / 64, nb = r % 64; const int dst = nb * 32; const int src = dst < 1536 ? dst : dst + 8;
;             transpose_item(a.in[I_WIN], 2056, 1024, WinT, a.in[I_PREMIX], scr, kb * 64, src, dst, lane); continue; }
.LBB0_43:
	s_ashr_i32 s2, s16, 31
	s_lshr_b32 s2, s2, 26
	s_add_i32 s2, s16, s2
	s_and_b32 s12, s2, 0xffffffc0
	s_sub_i32 s2, s16, s12
	s_lshl_b32 s4, s2, 5
	s_or_b32 s3, s4, 8
	s_cmp_lt_i32 s2, 48
	s_cselect_b32 s2, s4, s3
	s_ashr_i32 s13, s12, 31
	s_ashr_i32 s3, s2, 31
	v_mov_b32_e32 v31, s13
	v_or_b32_e32 v30, s12, v2
	v_lshl_add_u64 v[28:29], s[2:3], 2, v[20:21]
	v_lshl_add_u64 v[32:33], v[30:31], 2, s[10:11]
	s_mov_b32 s17, 0
	v_mov_b32_e32 v6, v49
	s_and_b64 s[36:37], s[8:9], exec
	s_cmp_eq_u64 s[36:37], exec
	s_cbranch_scc0 .LBB0_45
	v_add_u32_e32 v124, 0, v30
	v_mad_i64_i32 v[100:101], s[2:3], v124, s15, v[28:29]
	global_load_dword v108, v[100:101], off
	v_add_u32_e32 v125, 2, v30
	v_mad_i64_i32 v[102:103], s[2:3], v125, s15, v[28:29]
	global_load_dword v109, v[102:103], off
	v_add_u32_e32 v126, 4, v30
	v_mad_i64_i32 v[104:105], s[2:3], v126, s15, v[28:29]
	global_load_dword v110, v[104:105], off
	v_add_u32_e32 v127, 6, v30
	v_mad_i64_i32 v[106:107], s[2:3], v127, s15, v[28:29]
	global_load_dword v111, v[106:107], off
	v_add_u32_e32 v128, 8, v30
	v_mad_i64_i32 v[100:101], s[2:3], v128, s15, v[28:29]
	global_load_dword v112, v[100:101], off
	v_add_u32_e32 v129, 10, v30
	v_mad_i64_i32 v[102:103], s[2:3], v129, s15, v[28:29]
	global_load_dword v113, v[102:103], off
	v_add_u32_e32 v130, 12, v30
	v_mad_i64_i32 v[104:105], s[2:3], v130, s15, v[28:29]
	global_load_dword v114, v[104:105], off
	v_add_u32_e32 v131, 14, v30
	v_mad_i64_i32 v[106:107], s[2:3], v131, s15, v[28:29]
	global_load_dword v115, v[106:107], off
	v_add_u32_e32 v132, 16, v30
	v_mad_i64_i32 v[100:101], s[2:3], v132, s15, v[28:29]
	global_load_dword v116, v[100:101], off
	v_add_u32_e32 v133, 18, v30
	v_mad_i64_i32 v[102:103], s[2:3], v133, s15, v[28:29]
	global_load_dword v117, v[102:103], off
	v_add_u32_e32 v134, 20, v30
	v_mad_i64_i32 v[104:105], s[2:3], v134, s15, v[28:29]
	global_load_dword v118, v[104:105], off
	v_add_u32_e32 v135, 22, v30
	v_mad_i64_i32 v[106:107], s[2:3], v135, s15, v[28:29]
	global_load_dword v119, v[106:107], off
	v_add_u32_e32 v136, 24, v30
	v_mad_i64_i32 v[100:101], s[2:3], v136, s15, v[28:29]
	global_load_dword v120, v[100:101], off
	v_add_u32_e32 v137, 26, v30
	v_mad_i64_i32 v[102:103], s[2:3], v137, s15, v[28:29]
	global_load_dword v121, v[102:103], off
	v_add_u32_e32 v138, 28, v30
	v_mad_i64_i32 v[104:105], s[2:3], v138, s15, v[28:29]
	global_load_dword v122, v[104:105], off
	v_add_u32_e32 v139, 30, v30
	v_mad_i64_i32 v[106:107], s[2:3], v139, s15, v[28:29]
	global_load_dword v123, v[106:107], off
	global_load_dword v124, v[32:33], off offset:-56
	global_load_dword v125, v[32:33], off offset:-48
	global_load_dword v126, v[32:33], off offset:-40
	global_load_dword v127, v[32:33], off offset:-32
	global_load_dword v128, v[32:33], off offset:-24
	global_load_dword v129, v[32:33], off offset:-16
	global_load_dword v130, v[32:33], off offset:-8
	global_load_dword v131, v[32:33], off
	global_load_dword v132, v[32:33], off offset:8
	global_load_dword v133, v[32:33], off offset:16
	global_load_dword v134, v[32:33], off offset:24
	global_load_dword v135, v[32:33], off offset:32
	global_load_dword v136, v[32:33], off offset:40
	global_load_dword v137, v[32:33], off offset:48
	global_load_dword v138, v[32:33], off offset:56
	global_load_dword v139, v[32:33], off offset:64
	s_waitcnt vmcnt(15)
	v_mul_f32_e32 v108, v108, v124
	ds_write_b32 v6, v108
	s_waitcnt vmcnt(14)
	v_mul_f32_e32 v109, v109, v125
	ds_write_b32 v6, v109 offset:264
	s_waitcnt vmcnt(13)
	v_mul_f32_e32 v110, v110, v126
	ds_write_b32 v6, v110 offset:528
	s_waitcnt vmcnt(12)
	v_mul_f32_e32 v111, v111, v127
	ds_write_b32 v6, v111 offset:792
	s_waitcnt vmcnt(11)
	v_mul_f32_e32 v112, v112, v128
	ds_write_b32 v6, v112 offset:1056
	s_waitcnt vmcnt(10)
	v_mul_f32_e32 v113, v113, v129
	ds_write_b32 v6, v113 offset:1320
	s_waitcnt vmcnt(9)
	v_mul_f32_e32 v114, v114, v130
	ds_write_b32 v6, v114 offset:1584
	s_waitcnt vmcnt(8)
	v_mul_f32_e32 v115, v115, v131
	ds_write_b32 v6, v115 offset:1848
	s_waitcnt vmcnt(7)
	v_mul_f32_e32 v116, v116, v132
	ds_write_b32 v6, v116 offset:2112
	s_waitcnt vmcnt(6)
	v_mul_f32_e32 v117, v117, v133
	ds_write_b32 v6, v117 offset:2376
	s_waitcnt vmcnt(5)
	v_mul_f32_e32 v118, v118, v134
	ds_write_b32 v6, v118 offset:2640
	s_waitcnt vmcnt(4)
	v_mul_f32_e32 v119, v119, v135
	ds_write_b32 v6, v119 offset:2904
	s_waitcnt vmcnt(3)
	v_mul_f32_e32 v120, v120, v136
	ds_write_b32 v6, v120 offset:3168
	s_waitcnt vmcnt(2)
; #define LAS __attribute__((address_space(3)))
; __device__ __forceinline__ void transpose_item(const float* W, int ldw, int K, bf16_t* WT, const float* kscale, LAS float* scr, int k0, int srccol0, int dstrow0, int lane) {
; #pragma unroll 8
;     for (int i = 0; i < 32; ++i) { const int kk = 2 * i + (lane >> 5); float v = W[(size_t)(k0 + kk) * ldw + srccol0 + (lane & 31)]; if (kscale) v *= kscale[k0 + kk]; scr[kk * 33 + (lane & 31)] = v; }
;     asm volatile("s_waitcnt lgkmcnt(0)" ::: "memory");
	v_mul_f32_e32 v121, v121, v137
	ds_write_b32 v6, v121 offset:3432
	s_waitcnt vmcnt(1)
	v_mul_f32_e32 v122, v122, v138
	ds_write_b32 v6, v122 offset:3696
	s_waitcnt vmcnt(0)
	v_mul_f32_e32 v123, v123, v139
	ds_write_b32 v6, v123 offset:3960
	v_add_u32_e32 v124, 32, v30
	v_mad_i64_i32 v[100:101], s[2:3], v124, s15, v[28:29]
	global_load_dword v108, v[100:101], off
	v_add_u32_e32 v125, 34, v30
	v_mad_i64_i32 v[102:103], s[2:3], v125, s15, v[28:29]
	global_load_dword v109, v[102:103], off
	v_add_u32_e32 v126, 36, v30
	v_mad_i64_i32 v[104:105], s[2:3], v126, s15, v[28:29]
	global_load_dword v110, v[104:105], off
	v_add_u32_e32 v127, 38, v30
	v_mad_i64_i32 v[106:107], s[2:3], v127, s15, v[28:29]
	global_load_dword v111, v[106:107], off
	v_add_u32_e32 v128, 40, v30
	v_mad_i64_i32 v[100:101], s[2:3], v128, s15, v[28:29]
	global_load_dword v112, v[100:101], off
	v_add_u32_e32 v129, 42, v30
	v_mad_i64_i32 v[102:103], s[2:3], v129, s15, v[28:29]
	global_load_dword v113, v[102:103], off
	v_add_u32_e32 v130, 44, v30
	v_mad_i64_i32 v[104:105], s[2:3], v130, s15, v[28:29]
	global_load_dword v114, v[104:105], off
	v_add_u32_e32 v131, 46, v30
	v_mad_i64_i32 v[106:107], s[2:3], v131, s15, v[28:29]
	global_load_dword v115, v[106:107], off
	v_add_u32_e32 v132, 48, v30
	v_mad_i64_i32 v[100:101], s[2:3], v132, s15, v[28:29]
	global_load_dword v116, v[100:101], off
	v_add_u32_e32 v133, 50, v30
	v_mad_i64_i32 v[102:103], s[2:3], v133, s15, v[28:29]
	global_load_dword v117, v[102:103], off
	v_add_u32_e32 v134, 52, v30
	v_mad_i64_i32 v[104:105], s[2:3], v134, s15, v[28:29]
	global_load_dword v118, v[104:105], off
	v_add_u32_e32 v135, 54, v30
	v_mad_i64_i32 v[106:107], s[2:3], v135, s15, v[28:29]
	global_load_dword v119, v[106:107], off
	v_add_u32_e32 v136, 56, v30
	v_mad_i64_i32 v[100:101], s[2:3], v136, s15, v[28:29]
	global_load_dword v120, v[100:101], off
	v_add_u32_e32 v137, 58, v30
	v_mad_i64_i32 v[102:103], s[2:3], v137, s15, v[28:29]
	global_load_dword v121, v[102:103], off
	v_add_u32_e32 v138, 60, v30
	v_mad_i64_i32 v[104:105], s[2:3], v138, s15, v[28:29]
	global_load_dword v122, v[104:105], off
	v_add_u32_e32 v139, 62, v30
	v_mad_i64_i32 v[106:107], s[2:3], v139, s15, v[28:29]
	global_load_dword v123, v[106:107], off
	global_load_dword v124, v[32:33], off offset:72
	global_load_dword v125, v[32:33], off offset:80
	global_load_dword v126, v[32:33], off offset:88
	global_load_dword v127, v[32:33], off offset:96
	global_load_dword v128, v[32:33], off offset:104
	global_load_dword v129, v[32:33], off offset:112
	global_load_dword v130, v[32:33], off offset:120
	global_load_dword v131, v[32:33], off offset:128
	global_load_dword v132, v[32:33], off offset:136
	global_load_dword v133, v[32:33], off offset:144
	global_load_dword v134, v[32:33], off offset:152
	global_load_dword v135, v[32:33], off offset:160
	global_load_dword v136, v[32:33], off offset:168
	global_load_dword v137, v[32:33], off offset:176
	global_load_dword v138, v[32:33], off offset:184
	global_load_dword v139, v[32:33], off offset:192
	s_waitcnt vmcnt(15)
	v_mul_f32_e32 v108, v108, v124
	ds_write_b32 v6, v108 offset:4224
	s_waitcnt vmcnt(14)
	v_mul_f32_e32 v109, v109, v125
	ds_write_b32 v6, v109 offset:4488
	s_waitcnt vmcnt(13)
	v_mul_f32_e32 v110, v110, v126
	ds_write_b32 v6, v110 offset:4752
	s_waitcnt vmcnt(12)
	v_mul_f32_e32 v111, v111, v127
	ds_write_b32 v6, v111 offset:5016
	s_waitcnt vmcnt(11)
	v_mul_f32_e32 v112, v112, v128
	ds_write_b32 v6, v112 offset:5280
	s_waitcnt vmcnt(10)
	v_mul_f32_e32 v113, v113, v129
	ds_write_b32 v6, v113 offset:5544
	s_waitcnt vmcnt(9)
	v_mul_f32_e32 v114, v114, v130
	ds_write_b32 v6, v114 offset:5808
	s_waitcnt vmcnt(8)
	v_mul_f32_e32 v115, v115, v131
	ds_write_b32 v6, v115 offset:6072
	s_waitcnt vmcnt(7)
	v_mul_f32_e32 v116, v116, v132
	ds_write_b32 v6, v116 offset:6336
	s_waitcnt vmcnt(6)
	v_mul_f32_e32 v117, v117, v133
	ds_write_b32 v6, v117 offset:6600
	s_waitcnt vmcnt(5)
	v_mul_f32_e32 v118, v118, v134
	ds_write_b32 v6, v118 offset:6864
	s_waitcnt vmcnt(4)
	v_mul_f32_e32 v119, v119, v135
	ds_write_b32 v6, v119 offset:7128
	s_waitcnt vmcnt(3)
	v_mul_f32_e32 v120, v120, v136
	ds_write_b32 v6, v120 offset:7392
	s_waitcnt vmcnt(2)
	v_mul_f32_e32 v121, v121, v137
	ds_write_b32 v6, v121 offset:7656
	s_waitcnt vmcnt(1)
	v_mul_f32_e32 v122, v122, v138
	ds_write_b32 v6, v122 offset:7920
	s_waitcnt vmcnt(0)
	v_mul_f32_e32 v123, v123, v139
	ds_write_b32 v6, v123 offset:8184
	s_branch .LBB0_8
